# P7 and P11 residual+norm row loops rewritten by hand: all loads of a row issued together, gain vectors kept in registers (on top of 16x16x32 MLA + SWA staging)
# speedup vs baseline: 1.0075x; 1.0075x over previous
; __global__ void __launch_bounds__(512) fwd_mega(Args a) {
;     ...
;     if (IN(7)) {
;         for (int m = gw; m < NTOK; m += NGW) {
;             float sy = ssqY[(size_t)m * 32 + (lane & 31)];
; #pragma unroll
;             for (int o = 1; o < 32; o <<= 1) sy += __shfl_xor(sy, o);
;             const float rsy = 1.0f / sqrtf(sy * (1.f / DM) + EPS);
;             const f32x4* xr = (const f32x4*)(a.x + (size_t)m * DM) + lane; const unsigned long long* yr = (const unsigned long long*)(Y + (size_t)m * DM) + lane;
;             f32x4* outr = (f32x4*)(X1 + (size_t)m * DM) + lane; f32x4 v[8]; float s = 0.f;
; #pragma unroll
;             for (int j = 0; j < 8; ++j) { const f32x4 g = *((const f32x4*)a.g_mix_post + lane + 64 * j); const unsigned long long yw = yr[64 * j];
;                 const f32x4 yv = {__uint_as_float((unsigned)yw << 16), __uint_as_float((unsigned)yw & 0xffff0000u), __uint_as_float((unsigned)(yw >> 32) << 16), __uint_as_float((unsigned)(yw >> 32) & 0xffff0000u)};
;                 v[j] = xr[64 * j] + yv * rsy * g; outr[64 * j] = v[j];
;                 s += (v[j].x * v[j].x + v[j].y * v[j].y) + (v[j].z * v[j].z + v[j].w * v[j].w); }
.LBB0_879:
	s_cmp_lt_i32 s54, 8
	s_cselect_b64 s[4:5], -1, 0
	s_and_b64 s[4:5], s[4:5], s[0:1]
	s_cmp_lt_i32 s34, 0x8000
	s_cselect_b64 s[18:19], -1, 0
	s_and_b64 s[0:1], s[4:5], s[18:19]
	s_andn2_b64 vcc, exec, s[0:1]
	v_and_b32_e32 v163, 31, v162
	v_mbcnt_lo_u32_b32 v1, -1, 0
	v_lshlrev_b32_e32 v164, 4, v206
	s_cbranch_vccnz .LBB0_882
	v_mbcnt_hi_u32_b32 v2, -1, v1
	v_and_b32_e32 v3, 64, v2
	v_add_u32_e32 v3, 64, v3
	v_xor_b32_e32 v4, 1, v2
	v_cmp_lt_i32_e32 vcc, v4, v3
	v_mov_b32_e32 v165, 0
	v_lshl_add_u64 v[14:15], s[80:81], 0, v[164:165]
	v_cndmask_b32_e32 v4, v2, v4, vcc
	v_lshlrev_b32_e32 v48, 2, v4
	v_xor_b32_e32 v4, 2, v2
	v_cmp_lt_i32_e32 vcc, v4, v3
	v_lshl_add_u64 v[16:17], s[82:83], 0, v[164:165]
	s_mov_b64 s[0:1], 0x1000
	v_cndmask_b32_e32 v4, v2, v4, vcc
	v_lshlrev_b32_e32 v49, 2, v4
	v_xor_b32_e32 v4, 4, v2
	v_cmp_lt_i32_e32 vcc, v4, v3
	s_ashr_i32 s35, s34, 31
	v_lshl_add_u64 v[18:19], v[14:15], 0, s[0:1]
	v_cndmask_b32_e32 v4, v2, v4, vcc
	v_lshlrev_b32_e32 v50, 2, v4
	v_xor_b32_e32 v4, 8, v2
	v_cmp_lt_i32_e32 vcc, v4, v3
	v_lshl_add_u64 v[26:27], v[16:17], 0, s[0:1]
	s_lshl_b64 s[0:1], s[34:35], 12
	v_cndmask_b32_e32 v4, v2, v4, vcc
	v_lshlrev_b32_e32 v51, 2, v4
	v_xor_b32_e32 v4, 16, v2
	v_cmp_lt_i32_e32 vcc, v4, v3
	v_lshl_or_b32 v34, v206, 3, s0
	v_mov_b32_e32 v35, s1
	v_cndmask_b32_e32 v4, v2, v4, vcc
	v_lshlrev_b32_e32 v52, 2, v4
	v_xor_b32_e32 v4, 32, v2
	v_cmp_lt_i32_e32 vcc, v4, v3
	s_lshl_b64 s[0:1], s[34:35], 13
	v_or_b32_e32 v36, s0, v164
	v_cndmask_b32_e32 v2, v2, v4, vcc
	v_mov_b32_e32 v37, s1
	s_lshl_b64 s[0:1], s[34:35], 7
	v_lshlrev_b32_e32 v53, 2, v2
	s_mov_b64 s[6:7], 0x1400
	s_mov_b64 s[8:9], 0x1800
	s_mov_b64 s[12:13], 0x1c00
	s_ashr_i32 s57, s56, 31
	v_lshl_or_b32 v2, v163, 2, s0
	v_mov_b32_e32 v3, s1
	s_mov_b64 s[0:1], 0x8400000
	v_lshl_add_u64 v[20:21], v[14:15], 0, s[6:7]
	s_waitcnt lgkmcnt(0)
	v_lshl_add_u64 v[22:23], v[14:15], 0, s[8:9]
	v_lshl_add_u64 v[24:25], v[14:15], 0, s[12:13]
	v_lshl_add_u64 v[28:29], v[16:17], 0, s[6:7]
	v_lshl_add_u64 v[30:31], v[16:17], 0, s[8:9]
	v_lshl_add_u64 v[32:33], v[16:17], 0, s[12:13]
	s_lshl_b64 s[6:7], s[56:57], 12
	s_lshl_b64 s[12:13], s[56:57], 13
	v_lshl_add_u64 v[38:39], v[2:3], 0, s[0:1]
	s_lshl_b64 s[14:15], s[56:57], 7
	v_mov_b32_e32 v54, 0x358637bd
	s_mov_b32 s2, 0xf800000
	v_mov_b32_e32 v55, 0x260
	s_mov_b32 s8, 0x8c00000
	s_mov_b32 s9, 0xffff0000
	s_brev_b32 s16, 12
	s_movk_i32 s17, 0x1000
	s_mov_b32 s20, 0x30001000
	s_movk_i32 s21, 0x7fff
	s_brev_b32 s22, 20
	s_mov_b32 s23, s34
	s_mov_b32 s20, 0x1000
	s_mov_b32 s21, 0
	global_load_dwordx4 v[100:103], v[14:15], off offset:0
	global_load_dwordx4 v[168:171], v[16:17], off offset:0
	global_load_dwordx4 v[104:107], v[14:15], off offset:1024
	global_load_dwordx4 v[172:175], v[16:17], off offset:1024
	global_load_dwordx4 v[108:111], v[14:15], off offset:2048
	global_load_dwordx4 v[176:179], v[16:17], off offset:2048
	global_load_dwordx4 v[112:115], v[14:15], off offset:3072
	global_load_dwordx4 v[180:183], v[16:17], off offset:3072
	global_load_dwordx4 v[116:119], v[18:19], off
	global_load_dwordx4 v[184:187], v[26:27], off
	global_load_dwordx4 v[120:123], v[20:21], off
	global_load_dwordx4 v[188:191], v[28:29], off
	global_load_dwordx4 v[124:127], v[22:23], off
	global_load_dwordx4 v[192:195], v[30:31], off
	global_load_dwordx4 v[128:131], v[24:25], off
	global_load_dwordx4 v[196:199], v[32:33], off
.Lp7_row:
	v_lshl_add_u64 v[60:61], s[52:53], 0, v[34:35]
	v_lshl_add_u64 v[66:67], s[52:53], 0, v[36:37]
	v_lshl_add_u64 v[64:65], s[52:53], 0, v[38:39]
	v_lshl_add_u64 v[62:63], s[76:77], 0, v[36:37]
	v_add_co_u32_e32 v68, vcc, s22, v60
	s_nop 1
	v_addc_co_u32_e32 v69, vcc, 0, v61, vcc
	v_add_co_u32_e32 v60, vcc, s8, v60
	s_nop 1
	v_addc_co_u32_e32 v61, vcc, 0, v61, vcc
	v_add_co_u32_e32 v66, vcc, s16, v66
	s_nop 1
	v_addc_co_u32_e32 v67, vcc, 0, v67, vcc
	v_lshl_add_u64 v[70:71], v[62:63], 0, s[20:21]
	v_lshl_add_u64 v[72:73], v[66:67], 0, s[20:21]
	global_load_dword v98, v[64:65], off
	global_load_dwordx2 v[208:209], v[60:61], off offset:0
	global_load_dwordx2 v[210:211], v[60:61], off offset:512
	global_load_dwordx2 v[212:213], v[60:61], off offset:1024
	global_load_dwordx2 v[214:215], v[60:61], off offset:1536
	global_load_dwordx2 v[216:217], v[60:61], off offset:2048
	global_load_dwordx2 v[218:219], v[60:61], off offset:2560
	global_load_dwordx2 v[220:221], v[60:61], off offset:3072
	global_load_dwordx2 v[222:223], v[60:61], off offset:3584
	global_load_dwordx4 v[224:227], v[62:63], off offset:0
	global_load_dwordx4 v[228:231], v[62:63], off offset:1024
	global_load_dwordx4 v[232:235], v[62:63], off offset:2048
	global_load_dwordx4 v[236:239], v[62:63], off offset:3072
	global_load_dwordx4 v[240:243], v[70:71], off offset:0
	global_load_dwordx4 v[244:247], v[70:71], off offset:1024
	global_load_dwordx4 v[132:135], v[70:71], off offset:2048
	global_load_dwordx4 v[136:139], v[70:71], off offset:3072
	s_add_i32 s23, s23, s56
	v_lshl_add_u64 v[34:35], v[34:35], 0, s[6:7]
	v_lshl_add_u64 v[36:37], v[36:37], 0, s[12:13]
	v_lshl_add_u64 v[38:39], v[38:39], 0, s[14:15]
	s_waitcnt vmcnt(0)
	ds_bpermute_b32 v74, v48, v98
	s_waitcnt lgkmcnt(0)
	v_add_f32_e32 v98, v98, v74
	ds_bpermute_b32 v74, v49, v98
	s_waitcnt lgkmcnt(0)
	v_add_f32_e32 v98, v98, v74
	ds_bpermute_b32 v74, v50, v98
	s_waitcnt lgkmcnt(0)
	v_add_f32_e32 v98, v98, v74
	ds_bpermute_b32 v74, v51, v98
	s_waitcnt lgkmcnt(0)
	v_add_f32_e32 v98, v98, v74
	ds_bpermute_b32 v74, v52, v98
	s_waitcnt lgkmcnt(0)
; __device__ __forceinline__ unsigned pk2(float lo, float hi) { return f2bf(lo) | (f2bf(hi) << 16); }
; __global__ void __launch_bounds__(512) fwd_mega(Args a) {
;     ...
;             float sy = ssqY[(size_t)m * 32 + (lane & 31)];
; #pragma unroll
;             for (int o = 1; o < 32; o <<= 1) sy += __shfl_xor(sy, o);
;             const float rsy = 1.0f / sqrtf(sy * (1.f / DM) + EPS);
;             const f32x4* xr = (const f32x4*)(a.x + (size_t)m * DM) + lane; const unsigned long long* yr = (const unsigned long long*)(Y + (size_t)m * DM) + lane;
;             f32x4* outr = (f32x4*)(X1 + (size_t)m * DM) + lane; f32x4 v[8]; float s = 0.f;
; #pragma unroll
;             for (int j = 0; j < 8; ++j) { const f32x4 g = *((const f32x4*)a.g_mix_post + lane + 64 * j); const unsigned long long yw = yr[64 * j];
;                 const f32x4 yv = {__uint_as_float((unsigned)yw << 16), __uint_as_float((unsigned)yw & 0xffff0000u), __uint_as_float((unsigned)(yw >> 32) << 16), __uint_as_float((unsigned)(yw >> 32) & 0xffff0000u)};
;                 v[j] = xr[64 * j] + yv * rsy * g; outr[64 * j] = v[j];
;                 s += (v[j].x * v[j].x + v[j].y * v[j].y) + (v[j].z * v[j].z + v[j].w * v[j].w); }
;             const float rs = 1.0f / sqrtf(wave_sum(s) * (1.f / DM) + EPS);
;             unsigned long long* o8 = (unsigned long long*)(H2 + (size_t)m * DM) + lane;
; #pragma unroll
;             for (int j = 0; j < 8; ++j) { const f32x4 g = *((const f32x4*)a.g_ffn_pre + lane + 64 * j);
;                 o8[64 * j] = (unsigned long long)pk2(v[j].x * rs * g.x, v[j].y * rs * g.y) | ((unsigned long long)pk2(v[j].z * rs * g.z, v[j].w * rs * g.w) << 32); }
	v_add_f32_e32 v98, v98, v74
	v_fmamk_f32 v98, v98, 0x3a000000, v54
	v_mul_f32_e32 v74, 0x4f800000, v98
	v_cmp_gt_f32_e32 vcc, s2, v98
	s_nop 1
	v_cndmask_b32_e32 v98, v98, v74, vcc
	v_sqrt_f32_e32 v74, v98
	s_nop 0
	v_add_u32_e32 v75, -1, v74
	v_add_u32_e32 v76, 1, v74
	v_fma_f32 v77, -v75, v74, v98
	v_fma_f32 v78, -v76, v74, v98
	v_cmp_ge_f32_e64 s[0:1], 0, v77
	s_nop 1
	v_cndmask_b32_e64 v74, v74, v75, s[0:1]
	v_cmp_lt_f32_e64 s[0:1], 0, v78
	s_nop 1
	v_cndmask_b32_e64 v74, v74, v76, s[0:1]
	v_mul_f32_e32 v75, 0x37800000, v74
	v_cndmask_b32_e32 v74, v74, v75, vcc
	v_cmp_class_f32_e32 vcc, v98, v55
	s_nop 1
	v_cndmask_b32_e32 v98, v74, v98, vcc
	v_div_scale_f32 v74, s[0:1], v98, v98, 1.0
	v_rcp_f32_e32 v76, v74
	v_div_scale_f32 v75, vcc, 1.0, v98, 1.0
	v_fma_f32 v77, -v74, v76, 1.0
	v_fmac_f32_e32 v76, v77, v76
	v_mul_f32_e32 v77, v75, v76
	v_fma_f32 v78, -v74, v77, v75
	v_fmac_f32_e32 v77, v78, v76
	v_fma_f32 v74, -v74, v77, v75
	v_div_fmas_f32 v74, v74, v76, v77
	v_div_fixup_f32 v80, v74, v98, 1.0
	v_mov_b32_e32 v99, 0
	v_lshlrev_b32_e32 v84, 16, v208
	v_and_b32_e32 v85, 0xffff0000, v208
	v_lshlrev_b32_e32 v86, 16, v209
	v_and_b32_e32 v87, 0xffff0000, v209
	v_pk_mul_f32 v[84:85], v[80:81], v[84:85] op_sel_hi:[0,1]
	v_pk_mul_f32 v[86:87], v[80:81], v[86:87] op_sel_hi:[0,1]
	v_pk_fma_f32 v[224:225], v[100:101], v[84:85], v[224:225]
	v_pk_fma_f32 v[226:227], v[102:103], v[86:87], v[226:227]
	global_store_dwordx4 v[66:67], v[224:227], off offset:0
	v_mul_f32_e32 v84, v225, v225
	v_mul_f32_e32 v85, v227, v227
	v_fmac_f32_e32 v84, v224, v224
	v_fmac_f32_e32 v85, v226, v226
	v_add_f32_e32 v84, v84, v85
	v_add_f32_e32 v99, v99, v84
	v_lshlrev_b32_e32 v84, 16, v210
	v_and_b32_e32 v85, 0xffff0000, v210
	v_lshlrev_b32_e32 v86, 16, v211
	v_and_b32_e32 v87, 0xffff0000, v211
	v_pk_mul_f32 v[84:85], v[80:81], v[84:85] op_sel_hi:[0,1]
	v_pk_mul_f32 v[86:87], v[80:81], v[86:87] op_sel_hi:[0,1]
	v_pk_fma_f32 v[228:229], v[104:105], v[84:85], v[228:229]
	v_pk_fma_f32 v[230:231], v[106:107], v[86:87], v[230:231]
	global_store_dwordx4 v[66:67], v[228:231], off offset:1024
	v_mul_f32_e32 v84, v229, v229
	v_mul_f32_e32 v85, v231, v231
	v_fmac_f32_e32 v84, v228, v228
	v_fmac_f32_e32 v85, v230, v230
	v_add_f32_e32 v84, v84, v85
	v_add_f32_e32 v99, v99, v84
	v_lshlrev_b32_e32 v84, 16, v212
	v_and_b32_e32 v85, 0xffff0000, v212
	v_lshlrev_b32_e32 v86, 16, v213
	v_and_b32_e32 v87, 0xffff0000, v213
	v_pk_mul_f32 v[84:85], v[80:81], v[84:85] op_sel_hi:[0,1]
	v_pk_mul_f32 v[86:87], v[80:81], v[86:87] op_sel_hi:[0,1]
	v_pk_fma_f32 v[232:233], v[108:109], v[84:85], v[232:233]
	v_pk_fma_f32 v[234:235], v[110:111], v[86:87], v[234:235]
	global_store_dwordx4 v[66:67], v[232:235], off offset:2048
	v_mul_f32_e32 v84, v233, v233
	v_mul_f32_e32 v85, v235, v235
	v_fmac_f32_e32 v84, v232, v232
	v_fmac_f32_e32 v85, v234, v234
	v_add_f32_e32 v84, v84, v85
	v_add_f32_e32 v99, v99, v84
	v_lshlrev_b32_e32 v84, 16, v214
	v_and_b32_e32 v85, 0xffff0000, v214
	v_lshlrev_b32_e32 v86, 16, v215
	v_and_b32_e32 v87, 0xffff0000, v215
	v_pk_mul_f32 v[84:85], v[80:81], v[84:85] op_sel_hi:[0,1]
	v_pk_mul_f32 v[86:87], v[80:81], v[86:87] op_sel_hi:[0,1]
	v_pk_fma_f32 v[236:237], v[112:113], v[84:85], v[236:237]
	v_pk_fma_f32 v[238:239], v[114:115], v[86:87], v[238:239]
	global_store_dwordx4 v[66:67], v[236:239], off offset:3072
	v_mul_f32_e32 v84, v237, v237
	v_mul_f32_e32 v85, v239, v239
	v_fmac_f32_e32 v84, v236, v236
	v_fmac_f32_e32 v85, v238, v238
	v_add_f32_e32 v84, v84, v85
	v_add_f32_e32 v99, v99, v84
	v_lshlrev_b32_e32 v84, 16, v216
	v_and_b32_e32 v85, 0xffff0000, v216
	v_lshlrev_b32_e32 v86, 16, v217
	v_and_b32_e32 v87, 0xffff0000, v217
	v_pk_mul_f32 v[84:85], v[80:81], v[84:85] op_sel_hi:[0,1]
	v_pk_mul_f32 v[86:87], v[80:81], v[86:87] op_sel_hi:[0,1]
	v_pk_fma_f32 v[240:241], v[116:117], v[84:85], v[240:241]
	v_pk_fma_f32 v[242:243], v[118:119], v[86:87], v[242:243]
	global_store_dwordx4 v[72:73], v[240:243], off offset:0
	v_mul_f32_e32 v84, v241, v241
	v_mul_f32_e32 v85, v243, v243
	v_fmac_f32_e32 v84, v240, v240
	v_fmac_f32_e32 v85, v242, v242
	v_add_f32_e32 v84, v84, v85
	v_add_f32_e32 v99, v99, v84
	v_lshlrev_b32_e32 v84, 16, v218
	v_and_b32_e32 v85, 0xffff0000, v218
	v_lshlrev_b32_e32 v86, 16, v219
	v_and_b32_e32 v87, 0xffff0000, v219
	v_pk_mul_f32 v[84:85], v[80:81], v[84:85] op_sel_hi:[0,1]
	v_pk_mul_f32 v[86:87], v[80:81], v[86:87] op_sel_hi:[0,1]
	v_pk_fma_f32 v[244:245], v[120:121], v[84:85], v[244:245]
	v_pk_fma_f32 v[246:247], v[122:123], v[86:87], v[246:247]
	global_store_dwordx4 v[72:73], v[244:247], off offset:1024
	v_mul_f32_e32 v84, v245, v245
	v_mul_f32_e32 v85, v247, v247
	v_fmac_f32_e32 v84, v244, v244
	v_fmac_f32_e32 v85, v246, v246
	v_add_f32_e32 v84, v84, v85
	v_add_f32_e32 v99, v99, v84
	v_lshlrev_b32_e32 v84, 16, v220
	v_and_b32_e32 v85, 0xffff0000, v220
	v_lshlrev_b32_e32 v86, 16, v221
	v_and_b32_e32 v87, 0xffff0000, v221
	v_pk_mul_f32 v[84:85], v[80:81], v[84:85] op_sel_hi:[0,1]
	v_pk_mul_f32 v[86:87], v[80:81], v[86:87] op_sel_hi:[0,1]
	v_pk_fma_f32 v[132:133], v[124:125], v[84:85], v[132:133]
	v_pk_fma_f32 v[134:135], v[126:127], v[86:87], v[134:135]
	global_store_dwordx4 v[72:73], v[132:135], off offset:2048
	v_mul_f32_e32 v84, v133, v133
	v_mul_f32_e32 v85, v135, v135
	v_fmac_f32_e32 v84, v132, v132
	v_fmac_f32_e32 v85, v134, v134
	v_add_f32_e32 v84, v84, v85
	v_add_f32_e32 v99, v99, v84
	v_lshlrev_b32_e32 v84, 16, v222
	v_and_b32_e32 v85, 0xffff0000, v222
	v_lshlrev_b32_e32 v86, 16, v223
	v_and_b32_e32 v87, 0xffff0000, v223
	v_pk_mul_f32 v[84:85], v[80:81], v[84:85] op_sel_hi:[0,1]
	v_pk_mul_f32 v[86:87], v[80:81], v[86:87] op_sel_hi:[0,1]
	v_pk_fma_f32 v[136:137], v[128:129], v[84:85], v[136:137]
	v_pk_fma_f32 v[138:139], v[130:131], v[86:87], v[138:139]
	global_store_dwordx4 v[72:73], v[136:139], off offset:3072
	v_mul_f32_e32 v84, v137, v137
	v_mul_f32_e32 v85, v139, v139
	v_fmac_f32_e32 v84, v136, v136
	v_fmac_f32_e32 v85, v138, v138
	v_add_f32_e32 v84, v84, v85
	v_add_f32_e32 v99, v99, v84
	ds_bpermute_b32 v74, v48, v99
	s_waitcnt lgkmcnt(0)
; __device__ __forceinline__ unsigned pk2(float lo, float hi) { return f2bf(lo) | (f2bf(hi) << 16); }
; __global__ void __launch_bounds__(512) fwd_mega(Args a) {
;     ...
;                 s += (v[j].x * v[j].x + v[j].y * v[j].y) + (v[j].z * v[j].z + v[j].w * v[j].w); }
;             const float rs = 1.0f / sqrtf(wave_sum(s) * (1.f / DM) + EPS);
;             unsigned long long* o8 = (unsigned long long*)(H2 + (size_t)m * DM) + lane;
; #pragma unroll
;             for (int j = 0; j < 8; ++j) { const f32x4 g = *((const f32x4*)a.g_ffn_pre + lane + 64 * j);
;                 o8[64 * j] = (unsigned long long)pk2(v[j].x * rs * g.x, v[j].y * rs * g.y) | ((unsigned long long)pk2(v[j].z * rs * g.z, v[j].w * rs * g.w) << 32); }
;         }
	v_add_f32_e32 v99, v99, v74
	ds_bpermute_b32 v74, v49, v99
	s_waitcnt lgkmcnt(0)
	v_add_f32_e32 v99, v99, v74
	ds_bpermute_b32 v74, v50, v99
	s_waitcnt lgkmcnt(0)
	v_add_f32_e32 v99, v99, v74
	ds_bpermute_b32 v74, v51, v99
	s_waitcnt lgkmcnt(0)
	v_add_f32_e32 v99, v99, v74
	ds_bpermute_b32 v74, v52, v99
	s_waitcnt lgkmcnt(0)
	v_add_f32_e32 v99, v99, v74
	ds_bpermute_b32 v74, v53, v99
	s_waitcnt lgkmcnt(0)
	v_add_f32_e32 v99, v99, v74
	v_fmamk_f32 v99, v99, 0x3a000000, v54
	v_mul_f32_e32 v74, 0x4f800000, v99
	v_cmp_gt_f32_e32 vcc, s2, v99
	s_nop 1
	v_cndmask_b32_e32 v99, v99, v74, vcc
	v_sqrt_f32_e32 v74, v99
	s_nop 0
	v_add_u32_e32 v75, -1, v74
	v_add_u32_e32 v76, 1, v74
	v_fma_f32 v77, -v75, v74, v99
	v_fma_f32 v78, -v76, v74, v99
	v_cmp_ge_f32_e64 s[0:1], 0, v77
	s_nop 1
	v_cndmask_b32_e64 v74, v74, v75, s[0:1]
	v_cmp_lt_f32_e64 s[0:1], 0, v78
	s_nop 1
	v_cndmask_b32_e64 v74, v74, v76, s[0:1]
	v_mul_f32_e32 v75, 0x37800000, v74
	v_cndmask_b32_e32 v74, v74, v75, vcc
	v_cmp_class_f32_e32 vcc, v99, v55
	s_nop 1
	v_cndmask_b32_e32 v99, v74, v99, vcc
	v_div_scale_f32 v74, s[0:1], v99, v99, 1.0
	v_rcp_f32_e32 v76, v74
	v_div_scale_f32 v75, vcc, 1.0, v99, 1.0
	v_fma_f32 v77, -v74, v76, 1.0
	v_fmac_f32_e32 v76, v77, v76
	v_mul_f32_e32 v77, v75, v76
	v_fma_f32 v78, -v74, v77, v75
	v_fmac_f32_e32 v77, v78, v76
	v_fma_f32 v74, -v74, v77, v75
	v_div_fmas_f32 v74, v74, v76, v77
	v_div_fixup_f32 v46, v74, v99, 1.0
	v_mul_f32_e32 v84, v46, v224
	v_mul_f32_e32 v85, v46, v225
	v_mul_f32_e32 v86, v46, v226
	v_mul_f32_e32 v87, v46, v227
	v_mul_f32_e32 v84, v168, v84
	v_mul_f32_e32 v85, v169, v85
	v_mul_f32_e32 v86, v170, v86
	v_mul_f32_e32 v87, v171, v87
	v_cvt_pk_bf16_f32 v84, v84, v85
	v_cvt_pk_bf16_f32 v85, v86, v87
	global_store_dwordx2 v[68:69], v[84:85], off offset:0
	s_nop 1
	v_mul_f32_e32 v84, v46, v228
	v_mul_f32_e32 v85, v46, v229
	v_mul_f32_e32 v86, v46, v230
	v_mul_f32_e32 v87, v46, v231
	v_mul_f32_e32 v84, v172, v84
	v_mul_f32_e32 v85, v173, v85
	v_mul_f32_e32 v86, v174, v86
	v_mul_f32_e32 v87, v175, v87
	v_cvt_pk_bf16_f32 v84, v84, v85
	v_cvt_pk_bf16_f32 v85, v86, v87
	global_store_dwordx2 v[68:69], v[84:85], off offset:512
	s_nop 1
	v_mul_f32_e32 v84, v46, v232
	v_mul_f32_e32 v85, v46, v233
	v_mul_f32_e32 v86, v46, v234
	v_mul_f32_e32 v87, v46, v235
	v_mul_f32_e32 v84, v176, v84
	v_mul_f32_e32 v85, v177, v85
	v_mul_f32_e32 v86, v178, v86
	v_mul_f32_e32 v87, v179, v87
	v_cvt_pk_bf16_f32 v84, v84, v85
	v_cvt_pk_bf16_f32 v85, v86, v87
	global_store_dwordx2 v[68:69], v[84:85], off offset:1024
	s_nop 1
	v_mul_f32_e32 v84, v46, v236
	v_mul_f32_e32 v85, v46, v237
	v_mul_f32_e32 v86, v46, v238
	v_mul_f32_e32 v87, v46, v239
	v_mul_f32_e32 v84, v180, v84
	v_mul_f32_e32 v85, v181, v85
	v_mul_f32_e32 v86, v182, v86
	v_mul_f32_e32 v87, v183, v87
	v_cvt_pk_bf16_f32 v84, v84, v85
	v_cvt_pk_bf16_f32 v85, v86, v87
	global_store_dwordx2 v[68:69], v[84:85], off offset:1536
	s_nop 1
	v_mul_f32_e32 v84, v46, v240
	v_mul_f32_e32 v85, v46, v241
	v_mul_f32_e32 v86, v46, v242
	v_mul_f32_e32 v87, v46, v243
	v_mul_f32_e32 v84, v184, v84
	v_mul_f32_e32 v85, v185, v85
	v_mul_f32_e32 v86, v186, v86
	v_mul_f32_e32 v87, v187, v87
	v_cvt_pk_bf16_f32 v84, v84, v85
	v_cvt_pk_bf16_f32 v85, v86, v87
	global_store_dwordx2 v[68:69], v[84:85], off offset:2048
	s_nop 1
	v_mul_f32_e32 v84, v46, v244
	v_mul_f32_e32 v85, v46, v245
	v_mul_f32_e32 v86, v46, v246
	v_mul_f32_e32 v87, v46, v247
	v_mul_f32_e32 v84, v188, v84
	v_mul_f32_e32 v85, v189, v85
	v_mul_f32_e32 v86, v190, v86
	v_mul_f32_e32 v87, v191, v87
	v_cvt_pk_bf16_f32 v84, v84, v85
	v_cvt_pk_bf16_f32 v85, v86, v87
	global_store_dwordx2 v[68:69], v[84:85], off offset:2560
	s_nop 1
	v_mul_f32_e32 v84, v46, v132
	v_mul_f32_e32 v85, v46, v133
	v_mul_f32_e32 v86, v46, v134
	v_mul_f32_e32 v87, v46, v135
	v_mul_f32_e32 v84, v192, v84
	v_mul_f32_e32 v85, v193, v85
	v_mul_f32_e32 v86, v194, v86
	v_mul_f32_e32 v87, v195, v87
	v_cvt_pk_bf16_f32 v84, v84, v85
	v_cvt_pk_bf16_f32 v85, v86, v87
	global_store_dwordx2 v[68:69], v[84:85], off offset:3072
	s_nop 1
	v_mul_f32_e32 v84, v46, v136
	v_mul_f32_e32 v85, v46, v137
	v_mul_f32_e32 v86, v46, v138
	v_mul_f32_e32 v87, v46, v139
	v_mul_f32_e32 v84, v196, v84
	v_mul_f32_e32 v85, v197, v85
	v_mul_f32_e32 v86, v198, v86
	v_mul_f32_e32 v87, v199, v87
	v_cvt_pk_bf16_f32 v84, v84, v85
	v_cvt_pk_bf16_f32 v85, v86, v87
	global_store_dwordx2 v[68:69], v[84:85], off offset:3584
	s_nop 1
	s_cmp_lt_i32 s23, 0x8000
	s_cbranch_scc1 .Lp7_row

; __global__ void __launch_bounds__(512) fwd_mega(Args a) {
;     ...
;     if (IN(11)) {
;         for (int m = gw; m < NTOK; m += NGW) {
;             float sy = ssqY2[(size_t)m * 32 + (lane & 31)];
; #pragma unroll
;             for (int o = 1; o < 32; o <<= 1) sy += __shfl_xor(sy, o);
;             const float rsy = 1.0f / sqrtf(sy * (1.f / DM) + EPS);
;             const unsigned long long* yr = (const unsigned long long*)(Y2 + (size_t)m * DM) + lane; const f32x4* x1r = (const f32x4*)(X1 + (size_t)m * DM) + lane; f32x4* outr = (f32x4*)(a.out + (size_t)m * DM) + lane;
; #pragma unroll
;             for (int j = 0; j < 8; ++j) { const f32x4 g = *((const f32x4*)a.g_ffn_post + lane + 64 * j); const unsigned long long yw = yr[64 * j];
.LBB0_1049:
	s_cmp_lt_i32 s54, 12
	s_cselect_b64 s[2:3], -1, 0
	s_and_b64 s[0:1], s[2:3], s[0:1]
	s_and_b64 s[0:1], s[0:1], s[18:19]
	s_andn2_b64 vcc, exec, s[0:1]
	s_cbranch_vccnz .LBB0_1052
	v_mbcnt_hi_u32_b32 v2, -1, v1
	v_and_b32_e32 v0, 64, v2
	v_add_u32_e32 v3, 64, v0
	v_xor_b32_e32 v4, 1, v2
	v_cmp_lt_i32_e32 vcc, v4, v3
	v_mov_b32_e32 v165, 0
	v_lshl_add_u64 v[0:1], s[84:85], 0, v[164:165]
	v_cndmask_b32_e32 v4, v2, v4, vcc
	v_lshlrev_b32_e32 v20, 2, v4
	v_xor_b32_e32 v4, 2, v2
	v_cmp_lt_i32_e32 vcc, v4, v3
	s_mov_b64 s[0:1], 0x1000
	s_ashr_i32 s35, s34, 31
	v_cndmask_b32_e32 v4, v2, v4, vcc
	v_lshlrev_b32_e32 v21, 2, v4
	v_xor_b32_e32 v4, 4, v2
	v_cmp_lt_i32_e32 vcc, v4, v3
	s_ashr_i32 s57, s56, 31
	s_lshl_b64 s[2:3], s[56:57], 13
	v_cndmask_b32_e32 v4, v2, v4, vcc
	v_lshlrev_b32_e32 v22, 2, v4
	v_xor_b32_e32 v4, 8, v2
	v_cmp_lt_i32_e32 vcc, v4, v3
	s_lshl_b64 s[4:5], s[56:57], 7
	s_lshl_b64 s[6:7], s[56:57], 12
	v_cndmask_b32_e32 v4, v2, v4, vcc
	s_waitcnt lgkmcnt(0)
	v_lshlrev_b32_e32 v23, 2, v4
	v_xor_b32_e32 v4, 16, v2
	v_cmp_lt_i32_e32 vcc, v4, v3
	v_mov_b32_e32 v25, 0x358637bd
	s_mov_b32 s8, 0xf800000
	v_cndmask_b32_e32 v2, v2, v4, vcc
	v_lshlrev_b32_e32 v24, 2, v2
	v_lshl_add_u64 v[2:3], v[0:1], 0, s[0:1]
	s_mov_b64 s[0:1], 0x1400
	v_lshl_add_u64 v[4:5], v[0:1], 0, s[0:1]
	s_mov_b64 s[0:1], 0x1800
	v_lshl_add_u64 v[6:7], v[0:1], 0, s[0:1]
	s_mov_b64 s[0:1], 0x1c00
	v_lshl_add_u64 v[8:9], v[0:1], 0, s[0:1]
	s_lshl_b64 s[0:1], s[34:35], 13
	v_or_b32_e32 v10, s0, v164
	v_mov_b32_e32 v11, s1
	s_lshl_b64 s[0:1], s[34:35], 7
	v_lshl_or_b32 v12, v163, 2, s0
	v_mov_b32_e32 v13, s1
	s_mov_b64 s[0:1], 0x8800000
	v_lshl_add_u64 v[12:13], v[12:13], 0, s[0:1]
	s_lshl_b64 s[0:1], s[34:35], 12
	v_lshl_or_b32 v14, v206, 3, s0
	v_mov_b32_e32 v15, s1
	v_mov_b32_e32 v26, 0x260
	s_brev_b32 s9, 20
	s_brev_b32 s10, 12
	s_mov_b32 s11, 0x30001000
	s_movk_i32 s12, 0x1000
	s_mov_b32 s13, 0
	global_load_dwordx4 v[100:103], v[0:1], off offset:0
	global_load_dwordx4 v[104:107], v[0:1], off offset:1024
	global_load_dwordx4 v[108:111], v[0:1], off offset:2048
	global_load_dwordx4 v[112:115], v[0:1], off offset:3072
	global_load_dwordx4 v[116:119], v[2:3], off
	global_load_dwordx4 v[120:123], v[4:5], off
	global_load_dwordx4 v[124:127], v[6:7], off
	global_load_dwordx4 v[128:131], v[8:9], off
; __global__ void __launch_bounds__(512) fwd_mega(Args a) {
;     ...
;         for (int m = gw; m < NTOK; m += NGW) {
;             float sy = ssqY2[(size_t)m * 32 + (lane & 31)];
; #pragma unroll
;             for (int o = 1; o < 32; o <<= 1) sy += __shfl_xor(sy, o);
;             const float rsy = 1.0f / sqrtf(sy * (1.f / DM) + EPS);
;             const unsigned long long* yr = (const unsigned long long*)(Y2 + (size_t)m * DM) + lane; const f32x4* x1r = (const f32x4*)(X1 + (size_t)m * DM) + lane; f32x4* outr = (f32x4*)(a.out + (size_t)m * DM) + lane;
; #pragma unroll
;             for (int j = 0; j < 8; ++j) { const f32x4 g = *((const f32x4*)a.g_ffn_post + lane + 64 * j); const unsigned long long yw = yr[64 * j];
;                 const f32x4 yv = {__uint_as_float((unsigned)yw << 16), __uint_as_float((unsigned)yw & 0xffff0000u), __uint_as_float((unsigned)(yw >> 32) << 16), __uint_as_float((unsigned)(yw >> 32) & 0xffff0000u)};
;                 outr[64 * j] = x1r[64 * j] + yv * rsy * g; }
;         }
.Lp11_row:
	v_lshl_add_u64 v[16:17], s[52:53], 0, v[14:15]
	v_add_co_u32_e32 v16, vcc, s9, v16
	v_lshl_add_u64 v[18:19], s[52:53], 0, v[10:11]
	s_nop 0
	v_addc_co_u32_e32 v17, vcc, 0, v17, vcc
	v_add_co_u32_e32 v40, vcc, s10, v18
	v_lshl_add_u64 v[36:37], s[52:53], 0, v[12:13]
	s_nop 0
	v_addc_co_u32_e32 v41, vcc, 0, v19, vcc
	v_lshl_add_u64 v[38:39], s[30:31], 0, v[10:11]
	v_lshl_add_u64 v[48:49], v[40:41], 0, s[12:13]
	v_lshl_add_u64 v[50:51], v[38:39], 0, s[12:13]
	global_load_dword v27, v[36:37], off
	global_load_dwordx2 v[52:53], v[16:17], off offset:0
	global_load_dwordx2 v[54:55], v[16:17], off offset:512
	global_load_dwordx2 v[56:57], v[16:17], off offset:1024
	global_load_dwordx2 v[58:59], v[16:17], off offset:1536
	global_load_dwordx2 v[60:61], v[16:17], off offset:2048
	global_load_dwordx2 v[62:63], v[16:17], off offset:2560
	global_load_dwordx2 v[64:65], v[16:17], off offset:3072
	global_load_dwordx2 v[66:67], v[16:17], off offset:3584
	global_load_dwordx4 v[68:71], v[40:41], off offset:0
	global_load_dwordx4 v[72:75], v[40:41], off offset:1024
	global_load_dwordx4 v[76:79], v[40:41], off offset:2048
	global_load_dwordx4 v[80:83], v[40:41], off offset:3072
	global_load_dwordx4 v[84:87], v[48:49], off offset:0
	global_load_dwordx4 v[88:91], v[48:49], off offset:1024
	global_load_dwordx4 v[92:95], v[48:49], off offset:2048
	global_load_dwordx4 v[96:99], v[48:49], off offset:3072
	s_add_i32 s34, s34, s56
	v_lshl_add_u64 v[10:11], v[10:11], 0, s[2:3]
	v_lshl_add_u64 v[12:13], v[12:13], 0, s[4:5]
	v_lshl_add_u64 v[14:15], v[14:15], 0, s[6:7]
	s_waitcnt vmcnt(0)
	ds_bpermute_b32 v44, v20, v27
	s_waitcnt lgkmcnt(0)
	v_add_f32_e32 v27, v27, v44
	ds_bpermute_b32 v44, v21, v27
	s_waitcnt lgkmcnt(0)
	v_add_f32_e32 v27, v27, v44
	ds_bpermute_b32 v44, v22, v27
	s_waitcnt lgkmcnt(0)
	v_add_f32_e32 v27, v27, v44
	ds_bpermute_b32 v44, v23, v27
	s_waitcnt lgkmcnt(0)
	v_add_f32_e32 v27, v27, v44
	ds_bpermute_b32 v44, v24, v27
	s_waitcnt lgkmcnt(0)
	v_add_f32_e32 v27, v27, v44
	v_fmamk_f32 v27, v27, 0x3a000000, v25
	v_mul_f32_e32 v44, 0x4f800000, v27
	v_cmp_gt_f32_e32 vcc, s8, v27
	s_nop 1
	v_cndmask_b32_e32 v27, v27, v44, vcc
	v_sqrt_f32_e32 v44, v27
	s_nop 0
	v_add_u32_e32 v45, -1, v44
	v_add_u32_e32 v46, 1, v44
	v_fma_f32 v47, -v45, v44, v27
	v_fma_f32 v140, -v46, v44, v27
	v_cmp_ge_f32_e64 s[0:1], 0, v47
	s_nop 1
	v_cndmask_b32_e64 v44, v44, v45, s[0:1]
	v_cmp_lt_f32_e64 s[0:1], 0, v140
	s_nop 1
	v_cndmask_b32_e64 v44, v44, v46, s[0:1]
	v_mul_f32_e32 v45, 0x37800000, v44
	v_cndmask_b32_e32 v44, v44, v45, vcc
	v_cmp_class_f32_e32 vcc, v27, v26
	s_nop 1
	v_cndmask_b32_e32 v27, v44, v27, vcc
	v_div_scale_f32 v44, s[0:1], v27, v27, 1.0
	v_rcp_f32_e32 v46, v44
	v_div_scale_f32 v45, vcc, 1.0, v27, 1.0
	v_fma_f32 v47, -v44, v46, 1.0
	v_fmac_f32_e32 v46, v47, v46
	v_mul_f32_e32 v47, v45, v46
	v_fma_f32 v140, -v44, v47, v45
	v_fmac_f32_e32 v47, v140, v46
	v_fma_f32 v44, -v44, v47, v45
	v_div_fmas_f32 v44, v44, v46, v47
	v_div_fixup_f32 v44, v44, v27, 1.0
	v_lshlrev_b32_e32 v140, 16, v52
	v_and_b32_e32 v141, 0xffff0000, v52
	v_lshlrev_b32_e32 v142, 16, v53
	v_and_b32_e32 v143, 0xffff0000, v53
	v_pk_mul_f32 v[140:141], v[44:45], v[140:141] op_sel_hi:[0,1]
	v_pk_mul_f32 v[142:143], v[44:45], v[142:143] op_sel_hi:[0,1]
	v_pk_fma_f32 v[68:69], v[100:101], v[140:141], v[68:69]
	v_pk_fma_f32 v[70:71], v[102:103], v[142:143], v[70:71]
	global_store_dwordx4 v[38:39], v[68:71], off offset:0
	v_lshlrev_b32_e32 v140, 16, v54
	v_and_b32_e32 v141, 0xffff0000, v54
	v_lshlrev_b32_e32 v142, 16, v55
	v_and_b32_e32 v143, 0xffff0000, v55
	v_pk_mul_f32 v[140:141], v[44:45], v[140:141] op_sel_hi:[0,1]
	v_pk_mul_f32 v[142:143], v[44:45], v[142:143] op_sel_hi:[0,1]
	v_pk_fma_f32 v[72:73], v[104:105], v[140:141], v[72:73]
	v_pk_fma_f32 v[74:75], v[106:107], v[142:143], v[74:75]
	global_store_dwordx4 v[38:39], v[72:75], off offset:1024
	v_lshlrev_b32_e32 v140, 16, v56
	v_and_b32_e32 v141, 0xffff0000, v56
	v_lshlrev_b32_e32 v142, 16, v57
	v_and_b32_e32 v143, 0xffff0000, v57
	v_pk_mul_f32 v[140:141], v[44:45], v[140:141] op_sel_hi:[0,1]
	v_pk_mul_f32 v[142:143], v[44:45], v[142:143] op_sel_hi:[0,1]
	v_pk_fma_f32 v[76:77], v[108:109], v[140:141], v[76:77]
	v_pk_fma_f32 v[78:79], v[110:111], v[142:143], v[78:79]
	global_store_dwordx4 v[38:39], v[76:79], off offset:2048
	v_lshlrev_b32_e32 v140, 16, v58
	v_and_b32_e32 v141, 0xffff0000, v58
	v_lshlrev_b32_e32 v142, 16, v59
	v_and_b32_e32 v143, 0xffff0000, v59
	v_pk_mul_f32 v[140:141], v[44:45], v[140:141] op_sel_hi:[0,1]
	v_pk_mul_f32 v[142:143], v[44:45], v[142:143] op_sel_hi:[0,1]
	v_pk_fma_f32 v[80:81], v[112:113], v[140:141], v[80:81]
	v_pk_fma_f32 v[82:83], v[114:115], v[142:143], v[82:83]
	global_store_dwordx4 v[38:39], v[80:83], off offset:3072
	v_lshlrev_b32_e32 v140, 16, v60
	v_and_b32_e32 v141, 0xffff0000, v60
	v_lshlrev_b32_e32 v142, 16, v61
	v_and_b32_e32 v143, 0xffff0000, v61
	v_pk_mul_f32 v[140:141], v[44:45], v[140:141] op_sel_hi:[0,1]
	v_pk_mul_f32 v[142:143], v[44:45], v[142:143] op_sel_hi:[0,1]
	v_pk_fma_f32 v[84:85], v[116:117], v[140:141], v[84:85]
	v_pk_fma_f32 v[86:87], v[118:119], v[142:143], v[86:87]
	global_store_dwordx4 v[50:51], v[84:87], off offset:0
	v_lshlrev_b32_e32 v140, 16, v62
	v_and_b32_e32 v141, 0xffff0000, v62
	v_lshlrev_b32_e32 v142, 16, v63
	v_and_b32_e32 v143, 0xffff0000, v63
	v_pk_mul_f32 v[140:141], v[44:45], v[140:141] op_sel_hi:[0,1]
	v_pk_mul_f32 v[142:143], v[44:45], v[142:143] op_sel_hi:[0,1]
	v_pk_fma_f32 v[88:89], v[120:121], v[140:141], v[88:89]
	v_pk_fma_f32 v[90:91], v[122:123], v[142:143], v[90:91]
	global_store_dwordx4 v[50:51], v[88:91], off offset:1024
	v_lshlrev_b32_e32 v140, 16, v64
	v_and_b32_e32 v141, 0xffff0000, v64
	v_lshlrev_b32_e32 v142, 16, v65
	v_and_b32_e32 v143, 0xffff0000, v65
	v_pk_mul_f32 v[140:141], v[44:45], v[140:141] op_sel_hi:[0,1]
	v_pk_mul_f32 v[142:143], v[44:45], v[142:143] op_sel_hi:[0,1]
	v_pk_fma_f32 v[92:93], v[124:125], v[140:141], v[92:93]
	v_pk_fma_f32 v[94:95], v[126:127], v[142:143], v[94:95]
	global_store_dwordx4 v[50:51], v[92:95], off offset:2048
	v_lshlrev_b32_e32 v140, 16, v66
	v_and_b32_e32 v141, 0xffff0000, v66
	v_lshlrev_b32_e32 v142, 16, v67
	v_and_b32_e32 v143, 0xffff0000, v67
	v_pk_mul_f32 v[140:141], v[44:45], v[140:141] op_sel_hi:[0,1]
	v_pk_mul_f32 v[142:143], v[44:45], v[142:143] op_sel_hi:[0,1]
	v_pk_fma_f32 v[96:97], v[128:129], v[140:141], v[96:97]
	v_pk_fma_f32 v[98:99], v[130:131], v[142:143], v[98:99]
	global_store_dwordx4 v[50:51], v[96:99], off offset:3072
	s_cmp_lt_i32 s34, 0x8000
	s_cbranch_scc1 .Lp11_row
